# stack + non-temporal hint on the once-streamed f32 weight loads of P0 (weight conversion and adaLN GEMV)
# speedup vs baseline: 1.0022x; 1.0022x over previous
; #define LAS __attribute__((address_space(3)))
; __device__ __forceinline__ void p0_mod(LAS unsigned char* lds, const float* c, const float* w_ada, const float* b_ada, float* mod, int tid, int wave, int lane, int G) {
;     ...
;     for (int w = blockIdx.x; w < 256; w += G) {
;         const int cg0 = 144 * w, l = cg0 / MODW, n0 = cg0 % MODW;
;         if (lane < 36) {
;             const float* Wp = w_ada + (size_t)l * DM * MODW + (size_t)(wave * 256) * MODW + n0 + 4 * lane;
;             f32x4 a0 = {0.f, 0.f, 0.f, 0.f}, a1 = a0, a2 = a0, a3 = a0;
; #pragma unroll 8
;             for (int k = 0; k < 256; ++k) { const f32x4 wv = *(const f32x4*)(Wp + (size_t)k * MODW); const int kk = wave * 256 + k;
;                 a0 += wv * sl[kk]; a1 += wv * sl[DM + kk]; a2 += wv * sl[2 * DM + kk]; a3 += wv * sl[3 * DM + kk]; }
;             LAS float* r = red + (wave * 36 + lane) * 16;
;             *(LAS f32x4*)(r) = a0; *(LAS f32x4*)(r + 4) = a1; *(LAS f32x4*)(r + 8) = a2; *(LAS f32x4*)(r + 12) = a3;
.LBB0_25:
	v_lshl_add_u64 v[44:45], v[22:23], 0, s[40:41]
	v_add_co_u32_e32 v46, vcc, s3, v44
	global_load_dwordx4 v[28:31], v[44:45], off nt
	s_nop 0
	v_addc_co_u32_e32 v47, vcc, 0, v45, vcc
	v_add_co_u32_e32 v48, vcc, s12, v44
	v_addc_co_u32_e32 v49, vcc, 0, v45, vcc
	v_add_co_u32_e32 v60, vcc, s13, v44
	v_addc_co_u32_e32 v61, vcc, 0, v45, vcc
	v_add_co_u32_e32 v68, vcc, s14, v44
	v_addc_co_u32_e32 v69, vcc, 0, v45, vcc
	v_add_co_u32_e32 v72, vcc, s15, v44
	v_addc_co_u32_e32 v73, vcc, 0, v45, vcc
	v_add_co_u32_e32 v76, vcc, s16, v44
	s_add_u32 s40, s40, 0x90000
	s_nop 0
	v_addc_co_u32_e32 v77, vcc, 0, v45, vcc
	v_add_co_u32_e32 v80, vcc, s17, v44
	s_addc_u32 s41, s41, 0
	s_nop 0
	v_addc_co_u32_e32 v81, vcc, 0, v45, vcc
	global_load_dwordx4 v[44:47], v[46:47], off nt
	s_nop 0
	global_load_dwordx4 v[56:59], v[48:49], off nt
	global_load_dwordx4 v[64:67], v[60:61], off nt
	s_nop 0
	global_load_dwordx4 v[68:71], v[68:69], off nt
	s_nop 0
	global_load_dwordx4 v[72:75], v[72:73], off nt
	s_nop 0
	global_load_dwordx4 v[76:79], v[76:77], off nt
	s_nop 0
	global_load_dwordx4 v[80:83], v[80:81], off nt
	v_lshl_add_u64 v[160:161], v[22:23], 0, s[40:41]
	v_add_co_u32_e32 v162, vcc, s3, v160
	global_load_dwordx4 v[144:147], v[160:161], off nt
	s_nop 0
	v_addc_co_u32_e32 v163, vcc, 0, v161, vcc
	v_add_co_u32_e32 v164, vcc, s12, v160
	v_addc_co_u32_e32 v165, vcc, 0, v161, vcc
	v_add_co_u32_e32 v176, vcc, s13, v160
	v_addc_co_u32_e32 v177, vcc, 0, v161, vcc
	v_add_co_u32_e32 v184, vcc, s14, v160
	v_addc_co_u32_e32 v185, vcc, 0, v161, vcc
	v_add_co_u32_e32 v188, vcc, s15, v160
	v_addc_co_u32_e32 v189, vcc, 0, v161, vcc
	v_add_co_u32_e32 v192, vcc, s16, v160
	s_add_u32 s40, s40, 0x90000
	s_nop 0
	v_addc_co_u32_e32 v193, vcc, 0, v161, vcc
	v_add_co_u32_e32 v196, vcc, s17, v160
	s_addc_u32 s41, s41, 0
	s_nop 0
	v_addc_co_u32_e32 v197, vcc, 0, v161, vcc
	global_load_dwordx4 v[160:163], v[162:163], off nt
	s_nop 0
	global_load_dwordx4 v[172:175], v[164:165], off nt
	global_load_dwordx4 v[180:183], v[176:177], off nt
	s_nop 0
	global_load_dwordx4 v[184:187], v[184:185], off nt
	s_nop 0
	global_load_dwordx4 v[188:191], v[188:189], off nt
	s_nop 0
	global_load_dwordx4 v[192:195], v[192:193], off nt
	s_nop 0
	global_load_dwordx4 v[196:199], v[196:197], off nt
	v_mov_b32_e32 v51, s20
	s_nop 0
	ds_read_b128 v[32:35], v51
	ds_read_b128 v[36:39], v51 offset:16
	ds_read_b128 v[40:43], v51 offset:8192
	s_nop 0
	s_waitcnt lgkmcnt(0)
	v_mov_b32_e32 v54, v43
	ds_read_b128 v[84:87], v51 offset:8208
	ds_read_b128 v[88:91], v51 offset:16384
	ds_read_b128 v[92:95], v51 offset:16400
	ds_read_b128 v[96:99], v51 offset:24576
	ds_read_b128 v[100:103], v51 offset:24592
	v_mov_b32_e32 v48, v35
	s_waitcnt lgkmcnt(3)
	v_mov_b32_e32 v60, v91
	s_add_i32 s20, s20, 32
	s_waitcnt lgkmcnt(1)
	v_mov_b32_e32 v62, v99
	v_mov_b32_e32 v104, v39
	v_mov_b32_e32 v106, v87
	v_mov_b32_e32 v108, v95
	s_waitcnt lgkmcnt(0)
	v_mov_b32_e32 v110, v103
	s_waitcnt vmcnt(15)
	v_pk_fma_f32 v[4:5], v[30:31], v[32:33], v[4:5] op_sel_hi:[1,0,1]
	v_pk_fma_f32 v[2:3], v[28:29], v[32:33], v[2:3] op_sel_hi:[1,0,1]
	v_pk_fma_f32 v[8:9], v[30:31], v[40:41], v[8:9] op_sel_hi:[1,0,1]
	v_pk_fma_f32 v[6:7], v[28:29], v[40:41], v[6:7] op_sel_hi:[1,0,1]
	v_pk_fma_f32 v[16:17], v[30:31], v[88:89], v[16:17] op_sel_hi:[1,0,1]
	v_pk_fma_f32 v[14:15], v[28:29], v[88:89], v[14:15] op_sel_hi:[1,0,1]
	v_pk_fma_f32 v[12:13], v[30:31], v[96:97], v[12:13] op_sel_hi:[1,0,1]
	v_pk_fma_f32 v[10:11], v[28:29], v[96:97], v[10:11] op_sel_hi:[1,0,1]
	s_waitcnt vmcnt(14)
	v_pk_fma_f32 v[2:3], v[44:45], v[32:33], v[2:3] op_sel:[0,1,0]
	v_pk_fma_f32 v[4:5], v[46:47], v[32:33], v[4:5] op_sel:[0,1,0]
	v_pk_fma_f32 v[6:7], v[44:45], v[40:41], v[6:7] op_sel:[0,1,0]
	v_pk_fma_f32 v[8:9], v[46:47], v[40:41], v[8:9] op_sel:[0,1,0]
	v_pk_fma_f32 v[14:15], v[44:45], v[88:89], v[14:15] op_sel:[0,1,0]
	v_pk_fma_f32 v[16:17], v[46:47], v[88:89], v[16:17] op_sel:[0,1,0]
	v_pk_fma_f32 v[10:11], v[44:45], v[96:97], v[10:11] op_sel:[0,1,0]
	v_pk_fma_f32 v[12:13], v[46:47], v[96:97], v[12:13] op_sel:[0,1,0]
	s_waitcnt vmcnt(13)
	v_pk_fma_f32 v[4:5], v[58:59], v[34:35], v[4:5] op_sel_hi:[1,0,1]
	v_pk_fma_f32 v[2:3], v[56:57], v[34:35], v[2:3] op_sel_hi:[1,0,1]
	v_pk_fma_f32 v[8:9], v[58:59], v[42:43], v[8:9] op_sel_hi:[1,0,1]
	v_pk_fma_f32 v[6:7], v[56:57], v[42:43], v[6:7] op_sel_hi:[1,0,1]
	v_pk_fma_f32 v[16:17], v[58:59], v[90:91], v[16:17] op_sel_hi:[1,0,1]
	v_pk_fma_f32 v[14:15], v[56:57], v[90:91], v[14:15] op_sel_hi:[1,0,1]
	v_pk_fma_f32 v[12:13], v[58:59], v[98:99], v[12:13] op_sel_hi:[1,0,1]
	v_pk_fma_f32 v[10:11], v[56:57], v[98:99], v[10:11] op_sel_hi:[1,0,1]
	s_waitcnt vmcnt(12)
	v_pk_fma_f32 v[4:5], v[66:67], v[48:49], v[4:5] op_sel_hi:[1,0,1]
	v_pk_fma_f32 v[2:3], v[64:65], v[48:49], v[2:3] op_sel_hi:[1,0,1]
	v_pk_fma_f32 v[8:9], v[66:67], v[54:55], v[8:9] op_sel_hi:[1,0,1]
	v_pk_fma_f32 v[6:7], v[64:65], v[54:55], v[6:7] op_sel_hi:[1,0,1]
	v_pk_fma_f32 v[16:17], v[66:67], v[60:61], v[16:17] op_sel_hi:[1,0,1]
	v_pk_fma_f32 v[14:15], v[64:65], v[60:61], v[14:15] op_sel_hi:[1,0,1]
	v_pk_fma_f32 v[12:13], v[66:67], v[62:63], v[12:13] op_sel_hi:[1,0,1]
	v_pk_fma_f32 v[10:11], v[64:65], v[62:63], v[10:11] op_sel_hi:[1,0,1]
	s_waitcnt vmcnt(11)
	v_pk_fma_f32 v[4:5], v[70:71], v[36:37], v[4:5] op_sel_hi:[1,0,1]
	v_pk_fma_f32 v[2:3], v[68:69], v[36:37], v[2:3] op_sel_hi:[1,0,1]
	v_pk_fma_f32 v[8:9], v[70:71], v[84:85], v[8:9] op_sel_hi:[1,0,1]
	v_pk_fma_f32 v[6:7], v[68:69], v[84:85], v[6:7] op_sel_hi:[1,0,1]
	v_pk_fma_f32 v[16:17], v[70:71], v[92:93], v[16:17] op_sel_hi:[1,0,1]
	v_pk_fma_f32 v[14:15], v[68:69], v[92:93], v[14:15] op_sel_hi:[1,0,1]
	v_pk_fma_f32 v[12:13], v[70:71], v[100:101], v[12:13] op_sel_hi:[1,0,1]
	v_pk_fma_f32 v[10:11], v[68:69], v[100:101], v[10:11] op_sel_hi:[1,0,1]
	s_waitcnt vmcnt(10)
; #define LAS __attribute__((address_space(3)))
; __device__ __forceinline__ void p0_mod(LAS unsigned char* lds, const float* c, const float* w_ada, const float* b_ada, float* mod, int tid, int wave, int lane, int G) {
;     ...
;             for (int k = 0; k < 256; ++k) { const f32x4 wv = *(const f32x4*)(Wp + (size_t)k * MODW); const int kk = wave * 256 + k;
;                 a0 += wv * sl[kk]; a1 += wv * sl[DM + kk]; a2 += wv * sl[2 * DM + kk]; a3 += wv * sl[3 * DM + kk]; }
;             LAS float* r = red + (wave * 36 + lane) * 16;
;             *(LAS f32x4*)(r) = a0; *(LAS f32x4*)(r + 4) = a1; *(LAS f32x4*)(r + 8) = a2; *(LAS f32x4*)(r + 12) = a3;
	v_pk_fma_f32 v[4:5], v[74:75], v[36:37], v[4:5] op_sel:[0,1,0]
	v_pk_fma_f32 v[2:3], v[72:73], v[36:37], v[2:3] op_sel:[0,1,0]
	v_pk_fma_f32 v[8:9], v[74:75], v[84:85], v[8:9] op_sel:[0,1,0]
	v_pk_fma_f32 v[6:7], v[72:73], v[84:85], v[6:7] op_sel:[0,1,0]
	v_pk_fma_f32 v[16:17], v[74:75], v[92:93], v[16:17] op_sel:[0,1,0]
	v_pk_fma_f32 v[14:15], v[72:73], v[92:93], v[14:15] op_sel:[0,1,0]
	v_pk_fma_f32 v[12:13], v[74:75], v[100:101], v[12:13] op_sel:[0,1,0]
	v_pk_fma_f32 v[10:11], v[72:73], v[100:101], v[10:11] op_sel:[0,1,0]
	s_waitcnt vmcnt(9)
	v_pk_fma_f32 v[4:5], v[78:79], v[38:39], v[4:5] op_sel_hi:[1,0,1]
	v_pk_fma_f32 v[2:3], v[76:77], v[38:39], v[2:3] op_sel_hi:[1,0,1]
	v_pk_fma_f32 v[8:9], v[78:79], v[86:87], v[8:9] op_sel_hi:[1,0,1]
	v_pk_fma_f32 v[6:7], v[76:77], v[86:87], v[6:7] op_sel_hi:[1,0,1]
	v_pk_fma_f32 v[16:17], v[78:79], v[94:95], v[16:17] op_sel_hi:[1,0,1]
	v_pk_fma_f32 v[14:15], v[76:77], v[94:95], v[14:15] op_sel_hi:[1,0,1]
	v_pk_fma_f32 v[12:13], v[78:79], v[102:103], v[12:13] op_sel_hi:[1,0,1]
	v_pk_fma_f32 v[10:11], v[76:77], v[102:103], v[10:11] op_sel_hi:[1,0,1]
	s_waitcnt vmcnt(8)
	v_pk_fma_f32 v[4:5], v[82:83], v[104:105], v[4:5] op_sel_hi:[1,0,1]
	v_pk_fma_f32 v[2:3], v[80:81], v[104:105], v[2:3] op_sel_hi:[1,0,1]
	v_pk_fma_f32 v[8:9], v[82:83], v[106:107], v[8:9] op_sel_hi:[1,0,1]
	v_pk_fma_f32 v[6:7], v[80:81], v[106:107], v[6:7] op_sel_hi:[1,0,1]
	v_pk_fma_f32 v[16:17], v[82:83], v[108:109], v[16:17] op_sel_hi:[1,0,1]
	v_pk_fma_f32 v[14:15], v[80:81], v[108:109], v[14:15] op_sel_hi:[1,0,1]
	v_pk_fma_f32 v[12:13], v[82:83], v[110:111], v[12:13] op_sel_hi:[1,0,1]
	v_pk_fma_f32 v[10:11], v[80:81], v[110:111], v[10:11] op_sel_hi:[1,0,1]
	v_mov_b32_e32 v51, s20
	s_nop 0
	ds_read_b128 v[32:35], v51
	ds_read_b128 v[36:39], v51 offset:16
	ds_read_b128 v[40:43], v51 offset:8192
	s_nop 0
	s_waitcnt lgkmcnt(0)
	v_mov_b32_e32 v54, v43
	ds_read_b128 v[84:87], v51 offset:8208
	ds_read_b128 v[88:91], v51 offset:16384
	ds_read_b128 v[92:95], v51 offset:16400
	ds_read_b128 v[96:99], v51 offset:24576
	ds_read_b128 v[100:103], v51 offset:24592
	v_mov_b32_e32 v48, v35
	s_waitcnt lgkmcnt(3)
	v_mov_b32_e32 v60, v91
	s_add_i32 s20, s20, 32
	s_waitcnt lgkmcnt(1)
	v_mov_b32_e32 v62, v99
	v_mov_b32_e32 v104, v39
	v_mov_b32_e32 v106, v87
	v_mov_b32_e32 v108, v95
	s_waitcnt lgkmcnt(0)
	v_mov_b32_e32 v110, v103
	s_cmp_eq_u32 s40, 0x1200000
	s_waitcnt vmcnt(7)
	v_pk_fma_f32 v[4:5], v[146:147], v[32:33], v[4:5] op_sel_hi:[1,0,1]
	v_pk_fma_f32 v[2:3], v[144:145], v[32:33], v[2:3] op_sel_hi:[1,0,1]
	v_pk_fma_f32 v[8:9], v[146:147], v[40:41], v[8:9] op_sel_hi:[1,0,1]
	v_pk_fma_f32 v[6:7], v[144:145], v[40:41], v[6:7] op_sel_hi:[1,0,1]
	v_pk_fma_f32 v[16:17], v[146:147], v[88:89], v[16:17] op_sel_hi:[1,0,1]
	v_pk_fma_f32 v[14:15], v[144:145], v[88:89], v[14:15] op_sel_hi:[1,0,1]
	v_pk_fma_f32 v[12:13], v[146:147], v[96:97], v[12:13] op_sel_hi:[1,0,1]
	v_pk_fma_f32 v[10:11], v[144:145], v[96:97], v[10:11] op_sel_hi:[1,0,1]
	s_waitcnt vmcnt(6)
	v_pk_fma_f32 v[2:3], v[160:161], v[32:33], v[2:3] op_sel:[0,1,0]
	v_pk_fma_f32 v[4:5], v[162:163], v[32:33], v[4:5] op_sel:[0,1,0]
	v_pk_fma_f32 v[6:7], v[160:161], v[40:41], v[6:7] op_sel:[0,1,0]
	v_pk_fma_f32 v[8:9], v[162:163], v[40:41], v[8:9] op_sel:[0,1,0]
	v_pk_fma_f32 v[14:15], v[160:161], v[88:89], v[14:15] op_sel:[0,1,0]
	v_pk_fma_f32 v[16:17], v[162:163], v[88:89], v[16:17] op_sel:[0,1,0]
	v_pk_fma_f32 v[10:11], v[160:161], v[96:97], v[10:11] op_sel:[0,1,0]
	v_pk_fma_f32 v[12:13], v[162:163], v[96:97], v[12:13] op_sel:[0,1,0]
	s_waitcnt vmcnt(5)
; #define LAS __attribute__((address_space(3)))
; __device__ __forceinline__ void p0_mod(LAS unsigned char* lds, const float* c, const float* w_ada, const float* b_ada, float* mod, int tid, int wave, int lane, int G) {
;     ...
;             for (int k = 0; k < 256; ++k) { const f32x4 wv = *(const f32x4*)(Wp + (size_t)k * MODW); const int kk = wave * 256 + k;
;                 a0 += wv * sl[kk]; a1 += wv * sl[DM + kk]; a2 += wv * sl[2 * DM + kk]; a3 += wv * sl[3 * DM + kk]; }
;             LAS float* r = red + (wave * 36 + lane) * 16;
;             *(LAS f32x4*)(r) = a0; *(LAS f32x4*)(r + 4) = a1; *(LAS f32x4*)(r + 8) = a2; *(LAS f32x4*)(r + 12) = a3;
;         }
	v_pk_fma_f32 v[4:5], v[174:175], v[34:35], v[4:5] op_sel_hi:[1,0,1]
	v_pk_fma_f32 v[2:3], v[172:173], v[34:35], v[2:3] op_sel_hi:[1,0,1]
	v_pk_fma_f32 v[8:9], v[174:175], v[42:43], v[8:9] op_sel_hi:[1,0,1]
	v_pk_fma_f32 v[6:7], v[172:173], v[42:43], v[6:7] op_sel_hi:[1,0,1]
	v_pk_fma_f32 v[16:17], v[174:175], v[90:91], v[16:17] op_sel_hi:[1,0,1]
	v_pk_fma_f32 v[14:15], v[172:173], v[90:91], v[14:15] op_sel_hi:[1,0,1]
	v_pk_fma_f32 v[12:13], v[174:175], v[98:99], v[12:13] op_sel_hi:[1,0,1]
	v_pk_fma_f32 v[10:11], v[172:173], v[98:99], v[10:11] op_sel_hi:[1,0,1]
	s_waitcnt vmcnt(4)
	v_pk_fma_f32 v[4:5], v[182:183], v[48:49], v[4:5] op_sel_hi:[1,0,1]
	v_pk_fma_f32 v[2:3], v[180:181], v[48:49], v[2:3] op_sel_hi:[1,0,1]
	v_pk_fma_f32 v[8:9], v[182:183], v[54:55], v[8:9] op_sel_hi:[1,0,1]
	v_pk_fma_f32 v[6:7], v[180:181], v[54:55], v[6:7] op_sel_hi:[1,0,1]
	v_pk_fma_f32 v[16:17], v[182:183], v[60:61], v[16:17] op_sel_hi:[1,0,1]
	v_pk_fma_f32 v[14:15], v[180:181], v[60:61], v[14:15] op_sel_hi:[1,0,1]
	v_pk_fma_f32 v[12:13], v[182:183], v[62:63], v[12:13] op_sel_hi:[1,0,1]
	v_pk_fma_f32 v[10:11], v[180:181], v[62:63], v[10:11] op_sel_hi:[1,0,1]
	s_waitcnt vmcnt(3)
	v_pk_fma_f32 v[4:5], v[186:187], v[36:37], v[4:5] op_sel_hi:[1,0,1]
	v_pk_fma_f32 v[2:3], v[184:185], v[36:37], v[2:3] op_sel_hi:[1,0,1]
	v_pk_fma_f32 v[8:9], v[186:187], v[84:85], v[8:9] op_sel_hi:[1,0,1]
	v_pk_fma_f32 v[6:7], v[184:185], v[84:85], v[6:7] op_sel_hi:[1,0,1]
	v_pk_fma_f32 v[16:17], v[186:187], v[92:93], v[16:17] op_sel_hi:[1,0,1]
	v_pk_fma_f32 v[14:15], v[184:185], v[92:93], v[14:15] op_sel_hi:[1,0,1]
	v_pk_fma_f32 v[12:13], v[186:187], v[100:101], v[12:13] op_sel_hi:[1,0,1]
	v_pk_fma_f32 v[10:11], v[184:185], v[100:101], v[10:11] op_sel_hi:[1,0,1]
	s_waitcnt vmcnt(2)
	v_pk_fma_f32 v[4:5], v[190:191], v[36:37], v[4:5] op_sel:[0,1,0]
	v_pk_fma_f32 v[2:3], v[188:189], v[36:37], v[2:3] op_sel:[0,1,0]
	v_pk_fma_f32 v[8:9], v[190:191], v[84:85], v[8:9] op_sel:[0,1,0]
	v_pk_fma_f32 v[6:7], v[188:189], v[84:85], v[6:7] op_sel:[0,1,0]
	v_pk_fma_f32 v[16:17], v[190:191], v[92:93], v[16:17] op_sel:[0,1,0]
	v_pk_fma_f32 v[14:15], v[188:189], v[92:93], v[14:15] op_sel:[0,1,0]
	v_pk_fma_f32 v[12:13], v[190:191], v[100:101], v[12:13] op_sel:[0,1,0]
	v_pk_fma_f32 v[10:11], v[188:189], v[100:101], v[10:11] op_sel:[0,1,0]
	s_waitcnt vmcnt(1)
	v_pk_fma_f32 v[4:5], v[194:195], v[38:39], v[4:5] op_sel_hi:[1,0,1]
	v_pk_fma_f32 v[2:3], v[192:193], v[38:39], v[2:3] op_sel_hi:[1,0,1]
	v_pk_fma_f32 v[8:9], v[194:195], v[86:87], v[8:9] op_sel_hi:[1,0,1]
	v_pk_fma_f32 v[6:7], v[192:193], v[86:87], v[6:7] op_sel_hi:[1,0,1]
	v_pk_fma_f32 v[16:17], v[194:195], v[94:95], v[16:17] op_sel_hi:[1,0,1]
	v_pk_fma_f32 v[14:15], v[192:193], v[94:95], v[14:15] op_sel_hi:[1,0,1]
	v_pk_fma_f32 v[12:13], v[194:195], v[102:103], v[12:13] op_sel_hi:[1,0,1]
	v_pk_fma_f32 v[10:11], v[192:193], v[102:103], v[10:11] op_sel_hi:[1,0,1]
	s_waitcnt vmcnt(0)
	v_pk_fma_f32 v[4:5], v[198:199], v[104:105], v[4:5] op_sel_hi:[1,0,1]
	v_pk_fma_f32 v[2:3], v[196:197], v[104:105], v[2:3] op_sel_hi:[1,0,1]
	v_pk_fma_f32 v[8:9], v[198:199], v[106:107], v[8:9] op_sel_hi:[1,0,1]
	v_pk_fma_f32 v[6:7], v[196:197], v[106:107], v[6:7] op_sel_hi:[1,0,1]
	v_pk_fma_f32 v[16:17], v[198:199], v[108:109], v[16:17] op_sel_hi:[1,0,1]
	v_pk_fma_f32 v[14:15], v[196:197], v[108:109], v[14:15] op_sel_hi:[1,0,1]
	v_pk_fma_f32 v[12:13], v[198:199], v[110:111], v[12:13] op_sel_hi:[1,0,1]
	v_pk_fma_f32 v[10:11], v[196:197], v[110:111], v[10:11] op_sel_hi:[1,0,1]
	s_cbranch_scc0 .LBB0_25
	ds_write_b128 v24, v[2:5] offset:32768
	ds_write_b128 v24, v[6:9] offset:32784
	ds_write_b128 v24, v[14:17] offset:32800
	ds_write_b128 v24, v[10:13] offset:32816

; #define LAS __attribute__((address_space(3)))
; __device__ __forceinline__ void tr_item(const float* W, int ldw, int k0, int n0src, bf16* WT, int ldt, int drow0, int dk0, const float* gain, LAS float* scr, int lane) {
;     ...
;       for (int i = 0; i < 8; ++i) v[i] = *(const f32x4*)(W + (size_t)(k0 + 8 * i + (lane >> 3)) * ldw + n0src + 4 * (lane & 7));
; #pragma unroll
;       for (int i = 0; i < 8; ++i) { const int kk = 8 * i + (lane >> 3); f32x4 t = v[i]; if (gain) t = t * gain[k0 + kk];
;           LAS float* d = scr + kk * 33 + 4 * (lane & 7); d[0] = t[0]; d[1] = t[1]; d[2] = t[2]; d[3] = t[3]; } }
.Lpw_pdone_a:
	v_mad_u32_u24 v46, v40, s62, v43
	global_load_dwordx4 v[0:3], v46, s[60:61] nt
	v_add_u32_e32 v46, s63, v46
	global_load_dwordx4 v[4:7], v46, s[60:61] nt
	v_add_u32_e32 v46, s63, v46
	global_load_dwordx4 v[8:11], v46, s[60:61] nt
	v_add_u32_e32 v46, s63, v46
	global_load_dwordx4 v[12:15], v46, s[60:61] nt
	v_add_u32_e32 v46, s63, v46
	global_load_dwordx4 v[16:19], v46, s[60:61] nt
	v_add_u32_e32 v46, s63, v46
	global_load_dwordx4 v[20:23], v46, s[60:61] nt
	v_add_u32_e32 v46, s63, v46
	global_load_dwordx4 v[24:27], v46, s[60:61] nt
	v_add_u32_e32 v46, s63, v46
	global_load_dwordx4 v[28:31], v46, s[60:61] nt
	s_cmp_eq_u32 s69, 0
	s_cbranch_scc1 .Lpw_nog_a
	global_load_dword v32, v44, s[64:65]
	global_load_dword v33, v44, s[64:65] offset:32
	global_load_dword v34, v44, s[64:65] offset:64
	global_load_dword v35, v44, s[64:65] offset:96
	global_load_dword v36, v44, s[64:65] offset:128
	global_load_dword v37, v44, s[64:65] offset:160
	global_load_dword v38, v44, s[64:65] offset:192
	global_load_dword v39, v44, s[64:65] offset:224

; #define LAS __attribute__((address_space(3)))
; __device__ __forceinline__ void tr_item(const float* W, int ldw, int k0, int n0src, bf16* WT, int ldt, int drow0, int dk0, const float* gain, LAS float* scr, int lane) {
;     ...
;       for (int i = 0; i < 8; ++i) v[i] = *(const f32x4*)(W + (size_t)(k0 + 8 * i + (lane >> 3)) * ldw + n0src + 4 * (lane & 7));
; #pragma unroll
;       for (int i = 0; i < 8; ++i) { const int kk = 8 * i + (lane >> 3); f32x4 t = v[i]; if (gain) t = t * gain[k0 + kk];
;           LAS float* d = scr + kk * 33 + 4 * (lane & 7); d[0] = t[0]; d[1] = t[1]; d[2] = t[2]; d[3] = t[3]; } }
.Lpw_pdone_b:
	s_waitcnt lgkmcnt(0)
	v_mad_u32_u24 v46, v40, s62, v43
	global_load_dwordx4 v[0:3], v46, s[60:61] nt
	v_add_u32_e32 v46, s63, v46
	global_load_dwordx4 v[4:7], v46, s[60:61] nt
	v_add_u32_e32 v46, s63, v46
	global_load_dwordx4 v[8:11], v46, s[60:61] nt
	v_add_u32_e32 v46, s63, v46
	global_load_dwordx4 v[12:15], v46, s[60:61] nt
	v_add_u32_e32 v46, s63, v46
	global_load_dwordx4 v[16:19], v46, s[60:61] nt
	v_add_u32_e32 v46, s63, v46
	global_load_dwordx4 v[20:23], v46, s[60:61] nt
	v_add_u32_e32 v46, s63, v46
	global_load_dwordx4 v[24:27], v46, s[60:61] nt
	v_add_u32_e32 v46, s63, v46
	global_load_dwordx4 v[28:31], v46, s[60:61] nt
	s_cmp_eq_u32 s69, 0
	s_cbranch_scc1 .Lpw_nog_b
	global_load_dword v32, v44, s[64:65]
	global_load_dword v33, v44, s[64:65] offset:32
	global_load_dword v34, v44, s[64:65] offset:64
	global_load_dword v35, v44, s[64:65] offset:96
	global_load_dword v36, v44, s[64:65] offset:128
	global_load_dword v37, v44, s[64:65] offset:160
	global_load_dword v38, v44, s[64:65] offset:192
	global_load_dword v39, v44, s[64:65] offset:224
